# loop-edge edit: attention loop head, prompt items jump straight from the base computation to the load block (no flag test + second jump)
# speedup vs baseline: 1.0053x; 1.0053x over previous
; DI void attn_item(const Params& p, int l, int item, char* lds) {
;     ...
;   auto gload = [&](int j) {
;     const bf16_t* kb; size_t kld; const bf16_t* vb; size_t vld;
;     if (!samp) { kb = p.z + (size_t)(b * 4096 + j * 64) * NZ + C_K + h * 128; kld = NZ; vb = p.vtp + (size_t)((b * 4 + h) * 128) * 4096 + j * 64; vld = 4096; }
;     else if (j < 16) { kb = p.kc + (size_t)(b * 1024 + j * 64) * 512 + h * 128; kld = 512; vb = p.vct + (size_t)((b * 4 + h) * 128) * 1024 + j * 64; vld = 1024; }
;     else { kb = p.z + (size_t)(MP + b * 64) * NZ + C_K + h * 128; kld = NZ; vb = p.vts + (size_t)((b * 4 + h) * 128) * 64; vld = 64; }
; #pragma unroll
;     for (int i = 0; i < 4; ++i) {
;       const int c = tid + 256 * i;
;       const int mm = c >> 9, key = (c >> 3) & 63, d8 = (c & 7) * 8;
;       rk[i] = *(const u32x4*)(kb + (size_t)key * kld + mm * 64 + d8);
;       const int vd = c >> 3, k8 = (c & 7) * 8;
;       rv[i] = *(const u32x4*)(vb + (size_t)vd * vld + k8);
;     }
;   };
;     ...
;   for (int j = 0; j < nch; ++j) {
;     if (j + 1 < nch) gload(j + 1);
.LBB0_591:
	s_add_i32 s93, s39, 1
	s_cmp_lt_i32 s93, s44
	s_cselect_b64 s[40:41], -1, 0
	s_cmp_ge_i32 s93, s44
	s_cbranch_scc1 .LBB0_600
	s_and_b64 vcc, exec, s[0:1]
	s_mov_b64 s[2:3], -1
	s_cbranch_vccnz .LBB0_594
	s_lshl_b32 s96, s93, 6
	s_mul_i32 s3, s92, 0x3100
	s_mul_hi_i32 s2, s92, 0x3100
	s_add_u32 s3, s10, s3
	s_addc_u32 s2, s11, s2
	s_add_u32 s3, s3, s24
	s_addc_u32 s2, s2, 0
	s_add_u32 s42, s3, 0x1500
	s_addc_u32 s43, s2, 0
	s_lshl_b64 s[2:3], s[96:97], 1
	s_add_u32 s46, s50, s2
	s_addc_u32 s47, s51, s3
	s_mov_b64 s[2:3], 0x1880
	s_mov_b64 vcc, 0x1000
	s_branch .LBB0_599
